# instruction selection: DIFF exp(sub0) row-sum as a packed-add tree instead of a 16-add chain
# speedup vs baseline: 1.0049x; 1.0049x over previous
; #define MFMA(a, b, c) __builtin_amdgcn_mfma_f32_32x32x16_bf16((a), (b), (c), 0, 0, 0)
; DI u32 pk2(float a, float b) { f2_t v = {a, b}; bf2_t r = __builtin_convertvector(v, bf2_t); return __builtin_bit_cast(u32, r); }
; #define DIFF_MASK(sv, sub_) do { if (needmask) { _Pragma("unroll") for (int r = 0; r < 16; ++r) { const int kl_ = (sub_) * 32 + ((r < 8) ? (8 * g2 + r) : (16 + 8 * g2 + (r - 8))); \
;           if ((pki[kl_] >> 6) > (((int)qposf) >> 6)) sv[r] = -__builtin_inff(); } } } while (0)
; template <bool DIFF>
; DI void attn_phase(const AttnArgs& a, char* lds) {
;     ...
;           float ps = 0.f;
; #pragma unroll
;           for (int r = 0; r < 16; ++r) { s0[r] = __builtin_amdgcn_exp2f(s0[r]); ps += s0[r]; }
;           l_sum += ps;
;           asm volatile("" : "+v"(l_sum));
; #pragma unroll
;           for (int i = 0; i < NDS; ++i) { __builtin_amdgcn_sched_group_barrier(0x008, 1, 0); __builtin_amdgcn_sched_group_barrier(0x002, 9, 0); }
;         }
;         __builtin_amdgcn_sched_barrier(0);
;         {
;           bf16x8 vf[NM];
; #pragma unroll
;           for (int s2 = 0; s2 < 2; ++s2) {
; #pragma unroll
;             for (int m = 0; m < NM; ++m) vf[m] = *(const bf16x8*)(sb + voffb + m * 4096 + (((2 * s2) ^ vx) << 4));
;             u32x4 pw;
;             pw[0] = pk2(s0[8 * s2], s0[8 * s2 + 1]); pw[1] = pk2(s0[8 * s2 + 2], s0[8 * s2 + 3]);
;             pw[2] = pk2(s0[8 * s2 + 4], s0[8 * s2 + 5]); pw[3] = pk2(s0[8 * s2 + 6], s0[8 * s2 + 7]);
;             const bf16x8 pf = __builtin_bit_cast(bf16x8, pw);
; #pragma unroll
;             for (int m = 0; m < NM; ++m) o[m] = MFMA(vf[m], pf, o[m]);
;           }
;           DIFF_ALIBI(s1, 1);
;           DIFF_MASK(s1, 1);
.LBB0_605:
	v_bitop3_b32 v0, v0, v3, 7 bitop3:0x78
	v_lshlrev_b32_e32 v2, 7, v2
	v_and_b32_e32 v2, 0xf80, v2
	v_exp_f32_e32 v11, v11
	v_exp_f32_e32 v9, v9
	v_exp_f32_e32 v10, v10
	v_exp_f32_e32 v8, v8
	v_exp_f32_e32 v165, v7
	v_exp_f32_e32 v166, v6
	v_exp_f32_e32 v167, v5
	v_exp_f32_e32 v168, v4
	v_exp_f32_e32 v164, v164
	v_exp_f32_e32 v169, v162
	v_exp_f32_e32 v170, v160
	v_exp_f32_e32 v171, v161
	v_exp_f32_e32 v15, v15
	v_exp_f32_e32 v14, v14
	v_exp_f32_e32 v172, v13
	v_exp_f32_e32 v173, v12
	v_pk_add_f32 v[228:229], v[8:9], v[10:11]
	v_pk_add_f32 v[230:231], v[164:165], v[166:167]
	v_pk_add_f32 v[232:233], v[168:169], v[170:171]
	v_pk_add_f32 v[234:235], v[172:173], v[14:15]
	v_pk_add_f32 v[228:229], v[228:229], v[230:231]
	v_pk_add_f32 v[232:233], v[232:233], v[234:235]
	v_pk_add_f32 v[228:229], v[228:229], v[232:233]
	v_add_f32_e32 v3, v228, v229
	v_add_f32_e32 v162, v226, v3
	v_add_u32_e32 v160, s84, v2
	v_lshlrev_b32_e32 v161, 4, v0
	v_add_u32_e32 v0, v160, v161
	v_cvt_pk_bf16_f32 v6, v11, v9
	v_cvt_pk_bf16_f32 v7, v10, v8
	v_cvt_pk_bf16_f32 v8, v165, v166
	v_cvt_pk_bf16_f32 v9, v167, v168
	v_cvt_pk_bf16_f32 v10, v164, v169
	v_cvt_pk_bf16_f32 v11, v170, v171
	v_cvt_pk_bf16_f32 v12, v15, v14
	v_cvt_pk_bf16_f32 v13, v172, v173
	v_add_u32_e32 v14, 0x10180, v227
	v_xad_u32 v15, v161, 32, v160
	ds_read_b128 v[164:167], v14
	ds_read_b128 v[168:171], v14 offset:16
	ds_read_b128 v[172:175], v14 offset:64
	ds_read_b128 v[248:251], v14 offset:80
	ds_read_b128 v[2:5], v0 offset:32768
	ds_read_b128 v[228:231], v0 offset:36864
	ds_read_b128 v[232:235], v0 offset:40960
	ds_read_b128 v[236:239], v0 offset:45056
	ds_read_b128 v[240:243], v0 offset:49152
	ds_read_b128 v[244:247], v0 offset:53248
	s_and_b64 vcc, exec, s[8:9]
	s_waitcnt lgkmcnt(5)
	v_mfma_f32_32x32x16_bf16 v[128:143], v[2:5], v[6:9], v[128:143]
	ds_read_b128 v[2:5], v0 offset:57344
	v_sub_f32_e32 v164, v221, v164
	v_sub_f32_e32 v165, v221, v165
	v_fma_f32 v164, -v223, |v164|, v144
	v_fma_f32 v165, -v223, |v165|, v145
	s_waitcnt lgkmcnt(5)
	v_mfma_f32_32x32x16_bf16 v[112:127], v[228:231], v[6:9], v[112:127]
	ds_read_b128 v[228:231], v0 offset:61440
	v_sub_f32_e32 v166, v221, v166
	v_sub_f32_e32 v167, v221, v167
	v_fma_f32 v166, -v223, |v166|, v146
	v_fma_f32 v167, -v223, |v167|, v147
	s_waitcnt lgkmcnt(5)
	v_mfma_f32_32x32x16_bf16 v[96:111], v[232:235], v[6:9], v[96:111]
	ds_read_b128 v[232:235], v15 offset:32768
	v_sub_f32_e32 v168, v221, v168
	v_sub_f32_e32 v169, v221, v169
	v_fma_f32 v168, -v223, |v168|, v148
	v_fma_f32 v169, -v223, |v169|, v149
	s_waitcnt lgkmcnt(5)
	v_mfma_f32_32x32x16_bf16 v[80:95], v[236:239], v[6:9], v[80:95]
	ds_read_b128 v[236:239], v15 offset:36864
	v_sub_f32_e32 v170, v221, v170
	v_sub_f32_e32 v171, v221, v171
	v_fma_f32 v170, -v223, |v170|, v150
	v_fma_f32 v171, -v223, |v171|, v151
	s_waitcnt lgkmcnt(5)
	v_mfma_f32_32x32x16_bf16 v[64:79], v[240:243], v[6:9], v[64:79]
	ds_read_b128 v[240:243], v15 offset:40960
	v_sub_f32_e32 v172, v221, v172
	v_sub_f32_e32 v173, v221, v173
	v_fma_f32 v172, -v223, |v172|, v152
	v_fma_f32 v173, -v223, |v173|, v153
	s_waitcnt lgkmcnt(5)
	v_mfma_f32_32x32x16_bf16 v[48:63], v[244:247], v[6:9], v[48:63]
	ds_read_b128 v[244:247], v15 offset:45056
	v_sub_f32_e32 v174, v221, v174
	v_sub_f32_e32 v175, v221, v175
	v_fma_f32 v174, -v223, |v174|, v154
	v_fma_f32 v175, -v223, |v175|, v155
	s_waitcnt lgkmcnt(5)
	v_mfma_f32_32x32x16_bf16 v[32:47], v[2:5], v[6:9], v[32:47]
	ds_read_b128 v[2:5], v15 offset:49152
	v_sub_f32_e32 v248, v221, v248
	v_sub_f32_e32 v249, v221, v249
	v_fma_f32 v248, -v223, |v248|, v156
	v_fma_f32 v249, -v223, |v249|, v157
	s_waitcnt lgkmcnt(5)
	v_mfma_f32_32x32x16_bf16 v[16:31], v[228:231], v[6:9], v[16:31]
	ds_read_b128 v[228:231], v15 offset:53248
	v_sub_f32_e32 v250, v221, v250
	v_sub_f32_e32 v251, v221, v251
	v_fma_f32 v250, -v223, |v250|, v158
	v_fma_f32 v251, -v223, |v251|, v159
	s_cbranch_vccnz .Ldiff_nomask1
	ds_read_b128 v[146:149], v163 offset:128
	s_waitcnt lgkmcnt(0)
	v_ashrrev_i32_e32 v144, 6, v146
	v_cmp_le_i32_e32 vcc, v144, v224
	v_ashrrev_i32_e32 v144, 6, v147
	s_nop 0
	v_cndmask_b32_e32 v164, v216, v164, vcc
	v_cmp_le_i32_e32 vcc, v144, v224
	v_ashrrev_i32_e32 v144, 6, v148
	s_nop 0
	v_cndmask_b32_e32 v165, v216, v165, vcc
	v_cmp_le_i32_e32 vcc, v144, v224
	v_ashrrev_i32_e32 v144, 6, v149
	s_nop 0
	v_cndmask_b32_e32 v166, v216, v166, vcc
	v_cmp_le_i32_e32 vcc, v144, v224
	v_add_u32_e32 v144, 0x10090, v227
	ds_read_b128 v[146:149], v144
	v_cndmask_b32_e32 v167, v216, v167, vcc
	s_waitcnt lgkmcnt(0)
	v_ashrrev_i32_e32 v144, 6, v146
	v_cmp_le_i32_e32 vcc, v144, v224
	v_ashrrev_i32_e32 v144, 6, v147
	s_nop 0
	v_cndmask_b32_e32 v168, v216, v168, vcc
	v_cmp_le_i32_e32 vcc, v144, v224
	v_ashrrev_i32_e32 v144, 6, v148
	s_nop 0
	v_cndmask_b32_e32 v169, v216, v169, vcc
	v_cmp_le_i32_e32 vcc, v144, v224
	v_ashrrev_i32_e32 v144, 6, v149
	s_nop 0
	v_cndmask_b32_e32 v170, v216, v170, vcc
	v_cmp_le_i32_e32 vcc, v144, v224
	v_add_u32_e32 v144, 0x100c0, v227
	ds_read_b128 v[146:149], v144
	v_cndmask_b32_e32 v171, v216, v171, vcc
	s_waitcnt lgkmcnt(0)
	v_ashrrev_i32_e32 v144, 6, v146
	v_cmp_le_i32_e32 vcc, v144, v224
	v_ashrrev_i32_e32 v144, 6, v147
	s_nop 0
	v_cndmask_b32_e32 v172, v216, v172, vcc
	v_cmp_le_i32_e32 vcc, v144, v224
	v_ashrrev_i32_e32 v144, 6, v148
	s_nop 0
	v_cndmask_b32_e32 v173, v216, v173, vcc
	v_cmp_le_i32_e32 vcc, v144, v224
	v_ashrrev_i32_e32 v144, 6, v149
	s_nop 0
	v_cndmask_b32_e32 v174, v216, v174, vcc
	v_cmp_le_i32_e32 vcc, v144, v224
	v_add_u32_e32 v144, 0x100d0, v227
	ds_read_b128 v[146:149], v144
	v_cndmask_b32_e32 v175, v216, v175, vcc
	s_waitcnt lgkmcnt(0)
	v_ashrrev_i32_e32 v144, 6, v146
	v_cmp_le_i32_e32 vcc, v144, v224
	v_ashrrev_i32_e32 v144, 6, v147
	s_nop 0
	v_cndmask_b32_e32 v248, v216, v248, vcc
	v_cmp_le_i32_e32 vcc, v144, v224
	v_ashrrev_i32_e32 v144, 6, v148
	s_nop 0
	v_cndmask_b32_e32 v249, v216, v249, vcc
	v_cmp_le_i32_e32 vcc, v144, v224
	v_ashrrev_i32_e32 v144, 6, v149
	s_nop 0
	v_cndmask_b32_e32 v250, v216, v250, vcc
	v_cmp_le_i32_e32 vcc, v144, v224
	s_nop 1
	v_cndmask_b32_e32 v251, v216, v251, vcc
